# attention: tile j+2 global loads issued mid-step j right after the LDS tile write (no load block on the post-barrier path)
# baseline (speedup 1.0000x reference)
; #define ATT_LOAD(j) do { const int kb0_ = (j) < 4 ? b * NCTX + (j) * 64 : MCTX + b * SEQ + ((j) - 4) * 64; \
;             kreg[0] = *(const u32x4*)(kgp + (size_t)kb0_ * 1024); kreg[1] = *(const u32x4*)(kgp + (size_t)(kb0_ + 32) * 1024); \
;             vreg[0] = *(const u32x4*)(vgp + kb0_); vreg[1] = *(const u32x4*)(vgp + (size_t)64 * MALL + kb0_); } while (0)
; __device__ __forceinline__ void attn_phase(const LArgs& a, LAS unsigned char* lds) {
;     ...
;         for (int j = 0; j < NT; ++j) {
;             const int cur = j & 1;
;             if (j + 1 < NT) ATT_LOAD(j + 1);
.LBB0_324:
	s_cmpk_lg_i32 s21, 0x103
	s_mov_b32 s22, s0
	s_cselect_b64 s[0:1], -1, 0
	s_cmpk_lg_i32 s21, 1
	s_cbranch_scc1 .Lattn_noload
	s_cmp_lt_u32 s21, 3
	s_cselect_b32 s16, s19, s18
	s_ashr_i32 s17, s16, 31
	s_lshl_b64 s[24:25], s[16:17], 11
	v_lshl_add_u64 v[248:249], v[158:159], 0, s[24:25]
	s_or_b32 s24, s16, 32
	s_ashr_i32 s25, s24, 31
	s_lshl_b64 s[24:25], s[24:25], 11
	s_lshl_b64 s[16:17], s[16:17], 1
	v_lshl_add_u64 v[250:251], v[158:159], 0, s[24:25]
	global_load_dwordx4 v[128:131], v[248:249], off
	global_load_dwordx4 v[132:135], v[250:251], off
	v_lshl_add_u64 v[248:249], v[160:161], 0, s[16:17]
	v_lshl_add_u64 v[250:251], v[162:163], 0, s[16:17]
	global_load_dwordx4 v[136:139], v[248:249], off
	global_load_dwordx4 v[140:143], v[250:251], off

; __device__ __forceinline__ void attn_phase(const LArgs& a, LAS unsigned char* lds) {
;     ...
;             if (!late) ATT_PV(vcur, 1);
;             if (j + 1 < NT) ATT_STORE(cur ^ 1, vnext);
.Lattn_nowrite:
	s_cmpk_gt_i32 s21, 0x101
	s_cbranch_scc1 .Lattn_noload2
	s_cmp_lt_u32 s21, 2
	s_cselect_b32 s16, s19, s18
	s_add_i32 s16, s16, 64
	s_ashr_i32 s17, s16, 31
	s_lshl_b64 s[24:25], s[16:17], 11
	v_lshl_add_u64 v[180:181], v[158:159], 0, s[24:25]
	s_or_b32 s24, s16, 32
	s_ashr_i32 s25, s24, 31
	s_lshl_b64 s[24:25], s[24:25], 11
	s_lshl_b64 s[16:17], s[16:17], 1
	global_load_dwordx4 v[128:131], v[180:181], off
	v_lshl_add_u64 v[180:181], v[158:159], 0, s[24:25]
	global_load_dwordx4 v[132:135], v[180:181], off
	v_lshl_add_u64 v[180:181], v[160:161], 0, s[16:17]
	global_load_dwordx4 v[136:139], v[180:181], off
	v_lshl_add_u64 v[180:181], v[162:163], 0, s[16:17]
	global_load_dwordx4 v[140:143], v[180:181], off
